# masked attention tiles: stale-max threshold 8 (rescale only when needed) + exps of key-chunk k+1 overlapped with P.V MFMAs of chunk k
# baseline (speedup 1.0000x reference)
; __device__ __forceinline__ unsigned pk_bf16(float lo, float hi) { unsigned r; asm volatile("v_cvt_pk_bf16_f32 %0, %1, %2" : "=v"(r) : "v"(lo), "v"(hi)); return r; }
; __device__ __forceinline__ void attn_unit(int uv, const float* sink_l, const bf16_t* P, bf16_t* Y, ATT_LAS unsigned char* lds, const float* rpb_l, const float* qn_l, const float* kn_l) {
;     ...
;                 const float mt = rowmax32(p0, p1);
;                 if (__any(mt > m)) { const float mn = fmaxf(m, mt), alpha = __builtin_amdgcn_exp2f(m - mn); m = mn; lsum *= alpha;
; #pragma unroll
;                     for (int r = 0; r < 16; ++r) { o0[r] *= alpha; o1[r] *= alpha; } }
;                 float sum = 0.f;
; #pragma unroll
;                 for (int r = 0; r < 16; ++r) { p0[r] = __builtin_amdgcn_exp2f(p0[r] - m); p1[r] = __builtin_amdgcn_exp2f(p1[r] - m); sum += p0[r] + p1[r]; }
;                 lsum += sum;
;                 u32x4 pw[4];
; #pragma unroll
;                 for (int j = 0; j < 4; ++j) { pw[0][j] = pk_bf16(p0[2 * j], p0[2 * j + 1]); pw[1][j] = pk_bf16(p0[8 + 2 * j], p0[8 + 2 * j + 1]);
;                                               pw[2][j] = pk_bf16(p1[2 * j], p1[2 * j + 1]); pw[3][j] = pk_bf16(p1[8 + 2 * j], p1[8 + 2 * j + 1]); }
.Lmk_ctx_body:
	ds_read_b64_tr_b16 v[160:161], v242 offset:24576
	ds_read_b64_tr_b16 v[162:163], v242 offset:25088
	ds_read_b64_tr_b16 v[176:177], v242 offset:28672
	ds_read_b64_tr_b16 v[178:179], v242 offset:29184
	ds_read_b64_tr_b16 v[164:165], v242 offset:25600
	ds_read_b64_tr_b16 v[166:167], v242 offset:26112
	ds_read_b64_tr_b16 v[180:181], v242 offset:29696
	s_waitcnt lgkmcnt(14)
	v_mfma_f32_32x32x16_bf16 v[80:95], v[128:131], v[96:99], 0
	ds_read_b64_tr_b16 v[182:183], v242 offset:30208
	s_waitcnt lgkmcnt(14)
	v_mfma_f32_32x32x16_bf16 v[48:63], v[132:135], v[96:99], 0
	ds_read_b64_tr_b16 v[168:169], v242 offset:26624
	s_waitcnt lgkmcnt(14)
	v_mfma_f32_32x32x16_bf16 v[80:95], v[136:139], v[100:103], v[80:95]
	ds_read_b64_tr_b16 v[170:171], v242 offset:27136
	s_waitcnt lgkmcnt(14)
	v_mfma_f32_32x32x16_bf16 v[48:63], v[140:143], v[100:103], v[48:63]
	ds_read_b64_tr_b16 v[184:185], v242 offset:30720
	s_waitcnt lgkmcnt(14)
	v_mfma_f32_32x32x16_bf16 v[80:95], v[144:147], v[104:107], v[80:95]
	ds_read_b64_tr_b16 v[186:187], v242 offset:31232
	s_waitcnt lgkmcnt(14)
	v_mfma_f32_32x32x16_bf16 v[48:63], v[148:151], v[104:107], v[48:63]
	ds_read_b64_tr_b16 v[172:173], v242 offset:27648
	s_waitcnt lgkmcnt(14)
	v_mfma_f32_32x32x16_bf16 v[80:95], v[152:155], v[108:111], v[80:95]
	ds_read_b64_tr_b16 v[174:175], v242 offset:28160
	s_waitcnt lgkmcnt(14)
	v_mfma_f32_32x32x16_bf16 v[48:63], v[156:159], v[108:111], v[48:63]
	ds_read_b64_tr_b16 v[188:189], v242 offset:31744
	s_waitcnt lgkmcnt(14)
	ds_read_b64_tr_b16 v[190:191], v242 offset:32256
	s_nop 7
	s_nop 0
	v_max3_f32 v204, v80, v84, v88
	v_max3_f32 v205, v81, v85, v89
	v_max3_f32 v208, v82, v86, v90
	v_max3_f32 v209, v83, v87, v91
	v_max3_f32 v204, v204, v92, v48
	v_max3_f32 v205, v205, v93, v49
	v_max3_f32 v208, v208, v94, v50
	v_max3_f32 v209, v209, v95, v51
	v_max3_f32 v204, v204, v52, v56
	v_max3_f32 v205, v205, v53, v57
	v_max3_f32 v208, v208, v54, v58
	v_max3_f32 v209, v209, v55, v59
	v_max_f32_e32 v204, v204, v60
	v_max_f32_e32 v205, v205, v61
	v_max_f32_e32 v208, v208, v62
	v_max_f32_e32 v209, v209, v63
	v_max3_f32 v204, v204, v205, v208
	v_max_f32_e32 v204, v204, v209
	v_mov_b32_e32 v205, v204
	s_nop 1
	v_permlane32_swap_b32_e32 v204, v205
	v_max_f32_e32 v204, v204, v205
	v_add_f32_e32 v205, 0x41000000, v202
	v_cmp_gt_f32_e32 vcc, v204, v205
	s_cbranch_vccz .Lnb_ctx_norescale
	v_max_f32_e32 v205, v202, v204
	v_sub_f32_e32 v208, v202, v205
	v_exp_f32_e32 v208, v208
	v_mov_b32_e32 v202, v205
	v_pk_mul_f32 v[0:1], v[0:1], v[208:209] op_sel_hi:[1,0]
	v_pk_mul_f32 v[2:3], v[2:3], v[208:209] op_sel_hi:[1,0]
	v_pk_mul_f32 v[4:5], v[4:5], v[208:209] op_sel_hi:[1,0]
	v_pk_mul_f32 v[6:7], v[6:7], v[208:209] op_sel_hi:[1,0]
	v_pk_mul_f32 v[8:9], v[8:9], v[208:209] op_sel_hi:[1,0]
	v_pk_mul_f32 v[10:11], v[10:11], v[208:209] op_sel_hi:[1,0]
	v_pk_mul_f32 v[12:13], v[12:13], v[208:209] op_sel_hi:[1,0]
	v_pk_mul_f32 v[14:15], v[14:15], v[208:209] op_sel_hi:[1,0]
	v_pk_mul_f32 v[16:17], v[16:17], v[208:209] op_sel_hi:[1,0]
	v_pk_mul_f32 v[18:19], v[18:19], v[208:209] op_sel_hi:[1,0]
	v_pk_mul_f32 v[20:21], v[20:21], v[208:209] op_sel_hi:[1,0]
	v_pk_mul_f32 v[22:23], v[22:23], v[208:209] op_sel_hi:[1,0]
	v_pk_mul_f32 v[24:25], v[24:25], v[208:209] op_sel_hi:[1,0]
	v_pk_mul_f32 v[26:27], v[26:27], v[208:209] op_sel_hi:[1,0]
	v_pk_mul_f32 v[28:29], v[28:29], v[208:209] op_sel_hi:[1,0]
	v_pk_mul_f32 v[30:31], v[30:31], v[208:209] op_sel_hi:[1,0]
	v_mul_f32_e32 v124, v124, v208
.Lnb_ctx_norescale:
	v_sub_f32_e32 v80, v80, v202
	v_sub_f32_e32 v81, v81, v202
	v_sub_f32_e32 v82, v82, v202
	v_sub_f32_e32 v83, v83, v202
	v_sub_f32_e32 v84, v84, v202
	v_sub_f32_e32 v85, v85, v202
	v_sub_f32_e32 v86, v86, v202
	v_sub_f32_e32 v87, v87, v202
	v_sub_f32_e32 v88, v88, v202
	v_sub_f32_e32 v89, v89, v202
	v_sub_f32_e32 v90, v90, v202
	v_sub_f32_e32 v91, v91, v202
	v_sub_f32_e32 v92, v92, v202
	v_sub_f32_e32 v93, v93, v202
	v_sub_f32_e32 v94, v94, v202
	v_sub_f32_e32 v95, v95, v202
	v_sub_f32_e32 v48, v48, v202
	v_sub_f32_e32 v49, v49, v202
	v_sub_f32_e32 v50, v50, v202
	v_sub_f32_e32 v51, v51, v202
	v_sub_f32_e32 v52, v52, v202
	v_sub_f32_e32 v53, v53, v202
	v_sub_f32_e32 v54, v54, v202
	v_sub_f32_e32 v55, v55, v202
	v_sub_f32_e32 v56, v56, v202
	v_sub_f32_e32 v57, v57, v202
	v_sub_f32_e32 v58, v58, v202
	v_sub_f32_e32 v59, v59, v202
	v_sub_f32_e32 v60, v60, v202
	v_sub_f32_e32 v61, v61, v202
	v_sub_f32_e32 v62, v62, v202
	v_sub_f32_e32 v63, v63, v202
	v_exp_f32_e32 v80, v80
	v_exp_f32_e32 v81, v81
	v_exp_f32_e32 v82, v82
	v_exp_f32_e32 v83, v83
	v_exp_f32_e32 v84, v84
	v_exp_f32_e32 v85, v85
	v_exp_f32_e32 v86, v86
	v_exp_f32_e32 v87, v87
	s_nop 0
	v_cvt_pk_bf16_f32 v32, v80, v81
	v_cvt_pk_bf16_f32 v33, v82, v83
	v_cvt_pk_bf16_f32 v34, v84, v85
	v_cvt_pk_bf16_f32 v35, v86, v87
	s_nop 1
	s_waitcnt lgkmcnt(0)
; __device__ __forceinline__ void attn_unit(int uv, const float* sink_l, const bf16_t* P, bf16_t* Y, ATT_LAS unsigned char* lds, const float* rpb_l, const float* qn_l, const float* kn_l) {
;     ...
;                 else { const int qc = 32 * (wid & 1) + r32, cs = clampi(qc - 8, 0, 48); const ATT_LAS float* trow = tbl + (tl - qr + 7) * 31 + 15 - qc;
; #pragma unroll
;                     for (int r = 0; r < 16; ++r) { const int kcl = crow(r, hi);
;                         const float b0 = trow[kcl], b1 = trow[kcl + 32];
;                         p0[r] = ((unsigned)(kcl - cs) < 16u) ? p0[r] + b0 : NEGF;
;                         p1[r] = ((unsigned)(kcl + 32 - cs) < 16u) ? p1[r] + b1 : NEGF; } }
;                 const float mt = rowmax32(p0, p1);
;                 if (__any(mt > m)) { const float mn = fmaxf(m, mt), alpha = __builtin_amdgcn_exp2f(m - mn); m = mn; lsum *= alpha;
; #pragma unroll
;                     for (int r = 0; r < 16; ++r) { o0[r] *= alpha; o1[r] *= alpha; } }
;                 float sum = 0.f;
; #pragma unroll
;                 for (int r = 0; r < 16; ++r) { p0[r] = __builtin_amdgcn_exp2f(p0[r] - m); p1[r] = __builtin_amdgcn_exp2f(p1[r] - m); sum += p0[r] + p1[r]; }
;                 lsum += sum;
;                 u32x4 pw[4];
; #pragma unroll
;                 for (int j = 0; j < 4; ++j) { pw[0][j] = pk_bf16(p0[2 * j], p0[2 * j + 1]); pw[1][j] = pk_bf16(p0[8 + 2 * j], p0[8 + 2 * j + 1]);
;                                               pw[2][j] = pk_bf16(p1[2 * j], p1[2 * j + 1]); pw[3][j] = pk_bf16(p1[8 + 2 * j], p1[8 + 2 * j + 1]); }
;                 const ATT_LAS unsigned char* vb = Vb + vlane;
; #pragma unroll
;                 for (int s = 0; s < 4; ++s) {
;                     const bf16x8 pa = __builtin_bit_cast(bf16x8, pw[s]);
;                     { const s16x4 lo = vtr(vb + s * 1024), h4 = vtr(vb + s * 1024 + 512);
;                       const bf16x8 vf = (bf16x8){lo[0], lo[1], lo[2], lo[3], h4[0], h4[1], h4[2], h4[3]};
;                       o0 = __builtin_amdgcn_mfma_f32_32x32x16_bf16(vf, pa, o0, 0, 0, 0); }
;                     { const s16x4 lo = vtr(vb + 4096 + s * 1024), h4 = vtr(vb + 4096 + s * 1024 + 512);
;                       const bf16x8 vf = (bf16x8){lo[0], lo[1], lo[2], lo[3], h4[0], h4[1], h4[2], h4[3]};
;                       o1 = __builtin_amdgcn_mfma_f32_32x32x16_bf16(vf, pa, o1, 0, 0, 0); }
;                 }
	v_mfma_f32_32x32x16_bf16 v[0:15], v[160:163], v[32:35], v[0:15]
	v_exp_f32_e32 v88, v88
	v_exp_f32_e32 v89, v89
	v_exp_f32_e32 v90, v90
	v_exp_f32_e32 v91, v91
	v_mfma_f32_32x32x16_bf16 v[16:31], v[176:179], v[32:35], v[16:31]
	v_exp_f32_e32 v92, v92
	v_exp_f32_e32 v93, v93
	v_exp_f32_e32 v94, v94
	v_exp_f32_e32 v95, v95
	s_nop 0
	v_cvt_pk_bf16_f32 v36, v88, v89
	v_cvt_pk_bf16_f32 v37, v90, v91
	v_cvt_pk_bf16_f32 v38, v92, v93
	v_cvt_pk_bf16_f32 v39, v94, v95
	v_mov_b32_e32 v204, v80
	v_mov_b32_e32 v205, v81
	v_mov_b32_e32 v208, v82
	v_mov_b32_e32 v209, v83
	v_add_f32_e32 v204, v204, v84
	v_add_f32_e32 v205, v205, v85
	v_add_f32_e32 v208, v208, v86
	v_add_f32_e32 v209, v209, v87
	v_mfma_f32_32x32x16_bf16 v[0:15], v[164:167], v[36:39], v[0:15]
	v_exp_f32_e32 v48, v48
	v_exp_f32_e32 v49, v49
	v_exp_f32_e32 v50, v50
	v_exp_f32_e32 v51, v51
	v_mfma_f32_32x32x16_bf16 v[16:31], v[180:183], v[36:39], v[16:31]
	v_exp_f32_e32 v52, v52
	v_exp_f32_e32 v53, v53
	v_exp_f32_e32 v54, v54
	v_exp_f32_e32 v55, v55
	s_nop 0
	v_cvt_pk_bf16_f32 v40, v48, v49
	v_cvt_pk_bf16_f32 v41, v50, v51
	v_cvt_pk_bf16_f32 v42, v52, v53
	v_cvt_pk_bf16_f32 v43, v54, v55
	v_add_f32_e32 v204, v204, v88
	v_add_f32_e32 v205, v205, v89
	v_add_f32_e32 v208, v208, v90
	v_add_f32_e32 v209, v209, v91
	v_add_f32_e32 v204, v204, v92
	v_add_f32_e32 v205, v205, v93
	v_add_f32_e32 v208, v208, v94
	v_add_f32_e32 v209, v209, v95
	v_mfma_f32_32x32x16_bf16 v[0:15], v[168:171], v[40:43], v[0:15]
	v_exp_f32_e32 v56, v56
	v_exp_f32_e32 v57, v57
	v_exp_f32_e32 v58, v58
	v_exp_f32_e32 v59, v59
	v_mfma_f32_32x32x16_bf16 v[16:31], v[184:187], v[40:43], v[16:31]
	v_exp_f32_e32 v60, v60
	v_exp_f32_e32 v61, v61
	v_exp_f32_e32 v62, v62
	v_exp_f32_e32 v63, v63
	s_nop 0
	v_cvt_pk_bf16_f32 v44, v56, v57
	v_cvt_pk_bf16_f32 v45, v58, v59
	v_cvt_pk_bf16_f32 v46, v60, v61
	v_cvt_pk_bf16_f32 v47, v62, v63
	v_add_f32_e32 v204, v204, v48
	v_add_f32_e32 v205, v205, v49
	v_add_f32_e32 v208, v208, v50
	v_add_f32_e32 v209, v209, v51
	v_add_f32_e32 v204, v204, v52
	v_add_f32_e32 v205, v205, v53
	v_add_f32_e32 v208, v208, v54
	v_add_f32_e32 v209, v209, v55
	v_mfma_f32_32x32x16_bf16 v[0:15], v[172:175], v[44:47], v[0:15]
	v_mfma_f32_32x32x16_bf16 v[16:31], v[188:191], v[44:47], v[16:31]
	v_add_f32_e32 v204, v204, v56
	v_add_f32_e32 v205, v205, v57
	v_add_f32_e32 v208, v208, v58
	v_add_f32_e32 v209, v209, v59
	v_add_f32_e32 v204, v204, v60
	v_add_f32_e32 v205, v205, v61
	v_add_f32_e32 v208, v208, v62
	v_add_f32_e32 v209, v209, v63
	v_add_f32_e32 v204, v204, v205
	v_add_f32_e32 v208, v208, v209
	v_add_f32_e32 v204, v204, v208
	v_add_f32_e32 v124, v124, v204
	s_branch .Lmsk_tail
.Lmk_lat:
	s_and_b64 vcc, exec, s[2:3]
	s_cbranch_vccz .Lmsk_win
	v_readfirstlane_b32 vcc_lo, v192
	s_nop 0
	s_bitcmp1_b32 vcc_lo, 6
	s_cbranch_scc1 .Lnb_odd
	ds_read2_b32 v[32:33], v127 offset1:1
	ds_read2_b32 v[34:35], v127 offset0:2 offset1:3
	ds_read2_b32 v[36:37], v127 offset0:8 offset1:9
	ds_read2_b32 v[38:39], v127 offset0:10 offset1:11
	ds_read2_b32 v[40:41], v127 offset0:16 offset1:17
	ds_read2_b32 v[42:43], v127 offset0:18 offset1:19
	ds_read2_b32 v[44:45], v127 offset0:24 offset1:25
	s_waitcnt lgkmcnt(14)
	v_mfma_f32_32x32x16_bf16 v[80:95], v[128:131], v[96:99], 0
	ds_read2_b32 v[46:47], v127 offset0:26 offset1:27
	s_waitcnt lgkmcnt(14)
	v_mfma_f32_32x32x16_bf16 v[48:63], v[132:135], v[96:99], 0
	ds_read2_b32 v[64:65], v127 offset0:32 offset1:33
	s_waitcnt lgkmcnt(14)
	v_mfma_f32_32x32x16_bf16 v[80:95], v[136:139], v[100:103], v[80:95]
	ds_read2_b32 v[66:67], v127 offset0:34 offset1:35
	s_waitcnt lgkmcnt(14)
	v_mfma_f32_32x32x16_bf16 v[48:63], v[140:143], v[100:103], v[48:63]
	ds_read_b64_tr_b16 v[160:161], v242 offset:24576
	s_waitcnt lgkmcnt(14)
	v_mfma_f32_32x32x16_bf16 v[80:95], v[144:147], v[104:107], v[80:95]
	ds_read_b64_tr_b16 v[162:163], v242 offset:25088
	s_waitcnt lgkmcnt(14)
	v_mfma_f32_32x32x16_bf16 v[48:63], v[148:151], v[104:107], v[48:63]
	ds_read_b64_tr_b16 v[176:177], v242 offset:28672
	s_waitcnt lgkmcnt(14)
	v_mfma_f32_32x32x16_bf16 v[80:95], v[152:155], v[108:111], v[80:95]
	ds_read_b64_tr_b16 v[178:179], v242 offset:29184
	s_waitcnt lgkmcnt(14)
	v_mfma_f32_32x32x16_bf16 v[48:63], v[156:159], v[108:111], v[48:63]
	ds_read_b64_tr_b16 v[164:165], v242 offset:25600
	s_waitcnt lgkmcnt(14)
	ds_read_b64_tr_b16 v[166:167], v242 offset:26112
	s_nop 5
	v_add_f32_e32 v80, v80, v32
	v_add_f32_e32 v81, v81, v33
	v_cndmask_b32_e64 v80, v216, v80, s[0:1]
	v_cndmask_b32_e64 v81, v216, v81, s[4:5]
	s_waitcnt lgkmcnt(14)
	ds_read_b64_tr_b16 v[180:181], v242 offset:29696
	v_add_f32_e32 v82, v82, v34
	v_add_f32_e32 v83, v83, v35
	v_cndmask_b32_e64 v82, v216, v82, s[10:11]
	v_cndmask_b32_e64 v83, v216, v83, s[14:15]
	s_waitcnt lgkmcnt(14)
	ds_read_b64_tr_b16 v[182:183], v242 offset:30208
	v_add_f32_e32 v84, v84, v36
	v_add_f32_e32 v85, v85, v37
	v_cndmask_b32_e64 v84, v216, v84, s[18:19]
	v_cndmask_b32_e64 v85, v216, v85, s[22:23]
	s_waitcnt lgkmcnt(14)
	ds_read_b64_tr_b16 v[168:169], v242 offset:26624
	v_add_f32_e32 v86, v86, v38
	v_add_f32_e32 v87, v87, v39
	v_cndmask_b32_e64 v86, v216, v86, s[26:27]
	v_cndmask_b32_e64 v87, v216, v87, s[30:31]
	s_waitcnt lgkmcnt(14)
	ds_read_b64_tr_b16 v[170:171], v242 offset:27136
	v_add_f32_e32 v88, v88, v40
	v_add_f32_e32 v89, v89, v41
	v_cndmask_b32_e64 v88, v216, v88, s[76:77]
	v_cndmask_b32_e64 v89, v216, v89, s[40:41]
	s_waitcnt lgkmcnt(14)
	ds_read_b64_tr_b16 v[184:185], v242 offset:30720
	v_add_f32_e32 v90, v90, v42
	v_add_f32_e32 v91, v91, v43
	v_cndmask_b32_e64 v90, v216, v90, s[44:45]
	v_cndmask_b32_e64 v91, v216, v91, s[48:49]
	s_waitcnt lgkmcnt(14)
	ds_read_b64_tr_b16 v[186:187], v242 offset:31232
	v_add_f32_e32 v92, v92, v44
	v_add_f32_e32 v93, v93, v45
	v_cndmask_b32_e64 v92, v216, v92, s[52:53]
	v_cndmask_b32_e64 v93, v216, v93, s[56:57]
	s_waitcnt lgkmcnt(14)
	v_add_f32_e32 v94, v94, v46
	v_add_f32_e32 v95, v95, v47
	v_cndmask_b32_e64 v94, v216, v94, s[60:61]
	v_cndmask_b32_e64 v95, v216, v95, s[64:65]
	s_waitcnt lgkmcnt(13)
	v_add_f32_e32 v48, v48, v64
	v_add_f32_e32 v49, v49, v65
	v_cndmask_b32_e64 v48, v216, v48, s[68:69]
	v_cndmask_b32_e64 v49, v216, v49, s[8:9]
	s_waitcnt lgkmcnt(12)
	v_add_f32_e32 v50, v50, v66
	v_add_f32_e32 v51, v51, v67
	v_cndmask_b32_e64 v50, v216, v50, s[12:13]
	v_cndmask_b32_e64 v51, v216, v51, s[16:17]
	v_max3_f32 v204, v80, v84, v88
	v_max3_f32 v205, v81, v85, v89
	v_max3_f32 v208, v82, v86, v90
	v_max3_f32 v209, v83, v87, v91
	v_max3_f32 v204, v204, v92, v48
	v_max3_f32 v205, v205, v93, v49
	v_max3_f32 v208, v208, v94, v50
	v_max3_f32 v209, v209, v95, v51
	v_max3_f32 v204, v204, v205, v208
	v_max_f32_e32 v204, v204, v209
	v_mov_b32_e32 v205, v204
	s_nop 1
	v_permlane32_swap_b32_e32 v204, v205
	v_max_f32_e32 v204, v204, v205
	v_add_f32_e32 v205, 0x41000000, v202
	v_cmp_gt_f32_e32 vcc, v204, v205
	s_cbranch_vccz .Lnb_even_norescale
; #define ATT_LAS __attribute__((address_space(3)))
; __device__ __forceinline__ unsigned pk_bf16(float lo, float hi) { unsigned r; asm volatile("v_cvt_pk_bf16_f32 %0, %1, %2" : "=v"(r) : "v"(lo), "v"(hi)); return r; }
; __device__ __forceinline__ void attn_unit(int uv, const float* sink_l, const bf16_t* P, bf16_t* Y, ATT_LAS unsigned char* lds, const float* rpb_l, const float* qn_l, const float* kn_l) {
;     ...
;                 if (__any(mt > m)) { const float mn = fmaxf(m, mt), alpha = __builtin_amdgcn_exp2f(m - mn); m = mn; lsum *= alpha;
; #pragma unroll
;                     for (int r = 0; r < 16; ++r) { o0[r] *= alpha; o1[r] *= alpha; } }
;                 float sum = 0.f;
; #pragma unroll
;                 for (int r = 0; r < 16; ++r) { p0[r] = __builtin_amdgcn_exp2f(p0[r] - m); p1[r] = __builtin_amdgcn_exp2f(p1[r] - m); sum += p0[r] + p1[r]; }
;                 lsum += sum;
;                 u32x4 pw[4];
; #pragma unroll
;                 for (int j = 0; j < 4; ++j) { pw[0][j] = pk_bf16(p0[2 * j], p0[2 * j + 1]); pw[1][j] = pk_bf16(p0[8 + 2 * j], p0[8 + 2 * j + 1]);
;                                               pw[2][j] = pk_bf16(p1[2 * j], p1[2 * j + 1]); pw[3][j] = pk_bf16(p1[8 + 2 * j], p1[8 + 2 * j + 1]); }
;                 const ATT_LAS unsigned char* vb = Vb + vlane;
; #pragma unroll
;                 for (int s = 0; s < 4; ++s) {
;                     const bf16x8 pa = __builtin_bit_cast(bf16x8, pw[s]);
;                     { const s16x4 lo = vtr(vb + s * 1024), h4 = vtr(vb + s * 1024 + 512);
;                       const bf16x8 vf = (bf16x8){lo[0], lo[1], lo[2], lo[3], h4[0], h4[1], h4[2], h4[3]};
;                       o0 = __builtin_amdgcn_mfma_f32_32x32x16_bf16(vf, pa, o0, 0, 0, 0); }
;                     { const s16x4 lo = vtr(vb + 4096 + s * 1024), h4 = vtr(vb + 4096 + s * 1024 + 512);
;                       const bf16x8 vf = (bf16x8){lo[0], lo[1], lo[2], lo[3], h4[0], h4[1], h4[2], h4[3]};
;                       o1 = __builtin_amdgcn_mfma_f32_32x32x16_bf16(vf, pa, o1, 0, 0, 0); }
;                 }
	v_max_f32_e32 v205, v202, v204
	v_sub_f32_e32 v208, v202, v205
	v_exp_f32_e32 v208, v208
	v_mov_b32_e32 v202, v205
	v_pk_mul_f32 v[0:1], v[0:1], v[208:209] op_sel_hi:[1,0]
	v_pk_mul_f32 v[2:3], v[2:3], v[208:209] op_sel_hi:[1,0]
	v_pk_mul_f32 v[4:5], v[4:5], v[208:209] op_sel_hi:[1,0]
	v_pk_mul_f32 v[6:7], v[6:7], v[208:209] op_sel_hi:[1,0]
	v_pk_mul_f32 v[8:9], v[8:9], v[208:209] op_sel_hi:[1,0]
	v_pk_mul_f32 v[10:11], v[10:11], v[208:209] op_sel_hi:[1,0]
	v_pk_mul_f32 v[12:13], v[12:13], v[208:209] op_sel_hi:[1,0]
	v_pk_mul_f32 v[14:15], v[14:15], v[208:209] op_sel_hi:[1,0]
	v_pk_mul_f32 v[16:17], v[16:17], v[208:209] op_sel_hi:[1,0]
	v_pk_mul_f32 v[18:19], v[18:19], v[208:209] op_sel_hi:[1,0]
	v_pk_mul_f32 v[20:21], v[20:21], v[208:209] op_sel_hi:[1,0]
	v_pk_mul_f32 v[22:23], v[22:23], v[208:209] op_sel_hi:[1,0]
	v_pk_mul_f32 v[24:25], v[24:25], v[208:209] op_sel_hi:[1,0]
	v_pk_mul_f32 v[26:27], v[26:27], v[208:209] op_sel_hi:[1,0]
	v_pk_mul_f32 v[28:29], v[28:29], v[208:209] op_sel_hi:[1,0]
	v_pk_mul_f32 v[30:31], v[30:31], v[208:209] op_sel_hi:[1,0]
	v_mul_f32_e32 v124, v124, v208
.Lnb_even_norescale:
	v_sub_f32_e32 v80, v80, v202
	v_sub_f32_e32 v81, v81, v202
	v_sub_f32_e32 v82, v82, v202
	v_sub_f32_e32 v83, v83, v202
	v_sub_f32_e32 v84, v84, v202
	v_sub_f32_e32 v85, v85, v202
	v_sub_f32_e32 v86, v86, v202
	v_sub_f32_e32 v87, v87, v202
	v_sub_f32_e32 v88, v88, v202
	v_sub_f32_e32 v89, v89, v202
	v_sub_f32_e32 v90, v90, v202
	v_sub_f32_e32 v91, v91, v202
	v_sub_f32_e32 v92, v92, v202
	v_sub_f32_e32 v93, v93, v202
	v_sub_f32_e32 v94, v94, v202
	v_sub_f32_e32 v95, v95, v202
	v_sub_f32_e32 v48, v48, v202
	v_sub_f32_e32 v49, v49, v202
	v_sub_f32_e32 v50, v50, v202
	v_sub_f32_e32 v51, v51, v202
	v_mov_b32_e32 v42, 0
	v_mov_b32_e32 v43, 0
	v_exp_f32_e32 v80, v80
	v_exp_f32_e32 v81, v81
	v_exp_f32_e32 v82, v82
	v_exp_f32_e32 v83, v83
	v_exp_f32_e32 v84, v84
	v_exp_f32_e32 v85, v85
	v_exp_f32_e32 v86, v86
	v_exp_f32_e32 v87, v87
	s_nop 0
	v_cvt_pk_bf16_f32 v32, v80, v81
	v_cvt_pk_bf16_f32 v33, v82, v83
	v_cvt_pk_bf16_f32 v34, v84, v85
	v_cvt_pk_bf16_f32 v35, v86, v87
	s_nop 1
	s_waitcnt lgkmcnt(0)
	v_mfma_f32_32x32x16_bf16 v[0:15], v[160:163], v[32:35], v[0:15]
	v_exp_f32_e32 v88, v88
	v_exp_f32_e32 v89, v89
	v_exp_f32_e32 v90, v90
	v_exp_f32_e32 v91, v91
	v_mfma_f32_32x32x16_bf16 v[16:31], v[176:179], v[32:35], v[16:31]
	v_exp_f32_e32 v92, v92
	v_exp_f32_e32 v93, v93
	v_exp_f32_e32 v94, v94
	v_exp_f32_e32 v95, v95
	s_nop 0
	v_cvt_pk_bf16_f32 v36, v88, v89
	v_cvt_pk_bf16_f32 v37, v90, v91
	v_cvt_pk_bf16_f32 v38, v92, v93
	v_cvt_pk_bf16_f32 v39, v94, v95
	v_mov_b32_e32 v204, v80
	v_mov_b32_e32 v205, v81
	v_mov_b32_e32 v208, v82
	v_mov_b32_e32 v209, v83
	v_add_f32_e32 v204, v204, v84
	v_add_f32_e32 v205, v205, v85
	v_add_f32_e32 v208, v208, v86
	v_add_f32_e32 v209, v209, v87
	v_mfma_f32_32x32x16_bf16 v[0:15], v[164:167], v[36:39], v[0:15]
	v_exp_f32_e32 v48, v48
	v_exp_f32_e32 v49, v49
	v_mfma_f32_32x32x16_bf16 v[16:31], v[180:183], v[36:39], v[16:31]
	v_exp_f32_e32 v50, v50
	v_exp_f32_e32 v51, v51
	s_nop 0
	v_cvt_pk_bf16_f32 v40, v48, v49
	v_cvt_pk_bf16_f32 v41, v50, v51
	v_add_f32_e32 v204, v204, v88
	v_add_f32_e32 v205, v205, v89
	v_add_f32_e32 v208, v208, v90
	v_add_f32_e32 v209, v209, v91
	v_add_f32_e32 v204, v204, v92
	v_add_f32_e32 v205, v205, v93
	v_add_f32_e32 v208, v208, v94
	v_add_f32_e32 v209, v209, v95
	v_mfma_f32_32x32x16_bf16 v[0:15], v[168:171], v[40:43], v[0:15]
	v_mfma_f32_32x32x16_bf16 v[16:31], v[184:187], v[40:43], v[16:31]
	v_add_f32_e32 v204, v204, v48
	v_add_f32_e32 v205, v205, v49
	v_add_f32_e32 v208, v208, v50
	v_add_f32_e32 v209, v209, v51
	v_add_f32_e32 v204, v204, v205
	v_add_f32_e32 v208, v208, v209
	v_add_f32_e32 v204, v204, v208
	v_add_f32_e32 v124, v124, v204
	s_branch .Lmsk_tail
.Lnb_odd:
	ds_read2_b32 v[64:65], v127 offset0:32 offset1:33
	ds_read2_b32 v[66:67], v127 offset0:34 offset1:35
	ds_read2_b32 v[68:69], v127 offset0:40 offset1:41
	ds_read2_b32 v[70:71], v127 offset0:42 offset1:43
	ds_read2_b32 v[72:73], v127 offset0:48 offset1:49
	ds_read2_b32 v[74:75], v127 offset0:50 offset1:51
	ds_read2_b32 v[76:77], v127 offset0:56 offset1:57
	s_waitcnt lgkmcnt(14)
	v_mfma_f32_32x32x16_bf16 v[80:95], v[128:131], v[96:99], 0
	ds_read2_b32 v[78:79], v127 offset0:58 offset1:59
	s_waitcnt lgkmcnt(14)
	v_mfma_f32_32x32x16_bf16 v[48:63], v[132:135], v[96:99], 0
	ds_read2_b32 v[44:45], v127 offset0:24 offset1:25
	s_waitcnt lgkmcnt(14)
	v_mfma_f32_32x32x16_bf16 v[80:95], v[136:139], v[100:103], v[80:95]
	ds_read2_b32 v[46:47], v127 offset0:26 offset1:27
	s_waitcnt lgkmcnt(14)
	v_mfma_f32_32x32x16_bf16 v[48:63], v[140:143], v[100:103], v[48:63]
	ds_read_b64_tr_b16 v[164:165], v242 offset:25600
	s_waitcnt lgkmcnt(14)
	v_mfma_f32_32x32x16_bf16 v[80:95], v[144:147], v[104:107], v[80:95]
	ds_read_b64_tr_b16 v[166:167], v242 offset:26112
	s_waitcnt lgkmcnt(14)
	v_mfma_f32_32x32x16_bf16 v[48:63], v[148:151], v[104:107], v[48:63]
	ds_read_b64_tr_b16 v[180:181], v242 offset:29696
	s_waitcnt lgkmcnt(14)
	v_mfma_f32_32x32x16_bf16 v[80:95], v[152:155], v[108:111], v[80:95]
	ds_read_b64_tr_b16 v[182:183], v242 offset:30208
	s_waitcnt lgkmcnt(14)
	v_mfma_f32_32x32x16_bf16 v[48:63], v[156:159], v[108:111], v[48:63]
	ds_read_b64_tr_b16 v[168:169], v242 offset:26624
	s_waitcnt lgkmcnt(14)
	ds_read_b64_tr_b16 v[170:171], v242 offset:27136
	s_nop 7
	s_nop 0
	v_add_f32_e32 v48, v48, v64
	v_add_f32_e32 v49, v49, v65
	v_cndmask_b32_e64 v48, v216, v48, s[68:69]
	v_cndmask_b32_e64 v49, v216, v49, s[8:9]
	s_waitcnt lgkmcnt(14)
	ds_read_b64_tr_b16 v[184:185], v242 offset:30720
	v_add_f32_e32 v50, v50, v66
	v_add_f32_e32 v51, v51, v67
	v_cndmask_b32_e64 v50, v216, v50, s[12:13]
	v_cndmask_b32_e64 v51, v216, v51, s[16:17]
	s_waitcnt lgkmcnt(14)
; __device__ __forceinline__ void attn_unit(int uv, const float* sink_l, const bf16_t* P, bf16_t* Y, ATT_LAS unsigned char* lds, const float* rpb_l, const float* qn_l, const float* kn_l) {
;     ...
;                 else { const int qc = 32 * (wid & 1) + r32, cs = clampi(qc - 8, 0, 48); const ATT_LAS float* trow = tbl + (tl - qr + 7) * 31 + 15 - qc;
; #pragma unroll
;                     for (int r = 0; r < 16; ++r) { const int kcl = crow(r, hi);
;                         const float b0 = trow[kcl], b1 = trow[kcl + 32];
;                         p0[r] = ((unsigned)(kcl - cs) < 16u) ? p0[r] + b0 : NEGF;
;                         p1[r] = ((unsigned)(kcl + 32 - cs) < 16u) ? p1[r] + b1 : NEGF; } }
;                 const float mt = rowmax32(p0, p1);
;                 if (__any(mt > m)) { const float mn = fmaxf(m, mt), alpha = __builtin_amdgcn_exp2f(m - mn); m = mn; lsum *= alpha;
; #pragma unroll
;                     for (int r = 0; r < 16; ++r) { o0[r] *= alpha; o1[r] *= alpha; } }
;                 float sum = 0.f;
; #pragma unroll
;                 for (int r = 0; r < 16; ++r) { p0[r] = __builtin_amdgcn_exp2f(p0[r] - m); p1[r] = __builtin_amdgcn_exp2f(p1[r] - m); sum += p0[r] + p1[r]; }
;                 lsum += sum;
;                 u32x4 pw[4];
; #pragma unroll
;                 for (int j = 0; j < 4; ++j) { pw[0][j] = pk_bf16(p0[2 * j], p0[2 * j + 1]); pw[1][j] = pk_bf16(p0[8 + 2 * j], p0[8 + 2 * j + 1]);
;                                               pw[2][j] = pk_bf16(p1[2 * j], p1[2 * j + 1]); pw[3][j] = pk_bf16(p1[8 + 2 * j], p1[8 + 2 * j + 1]); }
;                 const ATT_LAS unsigned char* vb = Vb + vlane;
; #pragma unroll
;                 for (int s = 0; s < 4; ++s) {
;                     const bf16x8 pa = __builtin_bit_cast(bf16x8, pw[s]);
;                     { const s16x4 lo = vtr(vb + s * 1024), h4 = vtr(vb + s * 1024 + 512);
;                       const bf16x8 vf = (bf16x8){lo[0], lo[1], lo[2], lo[3], h4[0], h4[1], h4[2], h4[3]};
;                       o0 = __builtin_amdgcn_mfma_f32_32x32x16_bf16(vf, pa, o0, 0, 0, 0); }
;                     { const s16x4 lo = vtr(vb + 4096 + s * 1024), h4 = vtr(vb + 4096 + s * 1024 + 512);
;                       const bf16x8 vf = (bf16x8){lo[0], lo[1], lo[2], lo[3], h4[0], h4[1], h4[2], h4[3]};
;                       o1 = __builtin_amdgcn_mfma_f32_32x32x16_bf16(vf, pa, o1, 0, 0, 0); }
;                 }
	ds_read_b64_tr_b16 v[186:187], v242 offset:31232
	v_add_f32_e32 v52, v52, v68
	v_add_f32_e32 v53, v53, v69
	v_cndmask_b32_e64 v52, v216, v52, s[20:21]
	v_cndmask_b32_e64 v53, v216, v53, s[24:25]
	s_waitcnt lgkmcnt(14)
	ds_read_b64_tr_b16 v[172:173], v242 offset:27648
	v_add_f32_e32 v54, v54, v70
	v_add_f32_e32 v55, v55, v71
	v_cndmask_b32_e64 v54, v216, v54, s[28:29]
	v_cndmask_b32_e64 v55, v216, v55, s[94:95]
	s_waitcnt lgkmcnt(14)
	ds_read_b64_tr_b16 v[174:175], v242 offset:28160
	v_add_f32_e32 v56, v56, v72
	v_add_f32_e32 v57, v57, v73
	v_cndmask_b32_e64 v56, v216, v56, s[38:39]
	v_cndmask_b32_e64 v57, v216, v57, s[42:43]
	s_waitcnt lgkmcnt(14)
	ds_read_b64_tr_b16 v[188:189], v242 offset:31744
	v_add_f32_e32 v58, v58, v74
	v_add_f32_e32 v59, v59, v75
	v_cndmask_b32_e64 v58, v216, v58, s[46:47]
	v_cndmask_b32_e64 v59, v216, v59, s[50:51]
	s_waitcnt lgkmcnt(14)
	ds_read_b64_tr_b16 v[190:191], v242 offset:32256
	v_add_f32_e32 v60, v60, v76
	v_add_f32_e32 v61, v61, v77
	v_cndmask_b32_e64 v60, v216, v60, s[54:55]
	v_cndmask_b32_e64 v61, v216, v61, s[58:59]
	s_waitcnt lgkmcnt(14)
	v_add_f32_e32 v62, v62, v78
	v_add_f32_e32 v63, v63, v79
	v_cndmask_b32_e64 v62, v216, v62, s[62:63]
	v_cndmask_b32_e64 v63, v216, v63, s[66:67]
	s_waitcnt lgkmcnt(13)
	v_add_f32_e32 v92, v92, v44
	v_add_f32_e32 v93, v93, v45
	v_cndmask_b32_e64 v92, v216, v92, s[52:53]
	v_cndmask_b32_e64 v93, v216, v93, s[56:57]
	s_waitcnt lgkmcnt(12)
	v_add_f32_e32 v94, v94, v46
	v_add_f32_e32 v95, v95, v47
	v_cndmask_b32_e64 v94, v216, v94, s[60:61]
	v_cndmask_b32_e64 v95, v216, v95, s[64:65]
	v_max3_f32 v204, v92, v48, v52
	v_max3_f32 v205, v93, v49, v53
	v_max3_f32 v208, v94, v50, v54
	v_max3_f32 v209, v95, v51, v55
	v_max3_f32 v204, v204, v56, v60
	v_max3_f32 v205, v205, v57, v61
	v_max3_f32 v208, v208, v58, v62
	v_max3_f32 v209, v209, v59, v63
	v_max3_f32 v204, v204, v205, v208
	v_max_f32_e32 v204, v204, v209
	v_mov_b32_e32 v205, v204
	s_nop 1
	v_permlane32_swap_b32_e32 v204, v205
	v_max_f32_e32 v204, v204, v205
	v_add_f32_e32 v205, 0x41000000, v202
	v_cmp_gt_f32_e32 vcc, v204, v205
	s_cbranch_vccz .Lnb_odd_norescale
	v_max_f32_e32 v205, v202, v204
	v_sub_f32_e32 v208, v202, v205
	v_exp_f32_e32 v208, v208
	v_mov_b32_e32 v202, v205
	v_pk_mul_f32 v[0:1], v[0:1], v[208:209] op_sel_hi:[1,0]
	v_pk_mul_f32 v[2:3], v[2:3], v[208:209] op_sel_hi:[1,0]
	v_pk_mul_f32 v[4:5], v[4:5], v[208:209] op_sel_hi:[1,0]
	v_pk_mul_f32 v[6:7], v[6:7], v[208:209] op_sel_hi:[1,0]
	v_pk_mul_f32 v[8:9], v[8:9], v[208:209] op_sel_hi:[1,0]
	v_pk_mul_f32 v[10:11], v[10:11], v[208:209] op_sel_hi:[1,0]
	v_pk_mul_f32 v[12:13], v[12:13], v[208:209] op_sel_hi:[1,0]
	v_pk_mul_f32 v[14:15], v[14:15], v[208:209] op_sel_hi:[1,0]
	v_pk_mul_f32 v[16:17], v[16:17], v[208:209] op_sel_hi:[1,0]
	v_pk_mul_f32 v[18:19], v[18:19], v[208:209] op_sel_hi:[1,0]
	v_pk_mul_f32 v[20:21], v[20:21], v[208:209] op_sel_hi:[1,0]
	v_pk_mul_f32 v[22:23], v[22:23], v[208:209] op_sel_hi:[1,0]
	v_pk_mul_f32 v[24:25], v[24:25], v[208:209] op_sel_hi:[1,0]
	v_pk_mul_f32 v[26:27], v[26:27], v[208:209] op_sel_hi:[1,0]
	v_pk_mul_f32 v[28:29], v[28:29], v[208:209] op_sel_hi:[1,0]
	v_pk_mul_f32 v[30:31], v[30:31], v[208:209] op_sel_hi:[1,0]
	v_mul_f32_e32 v124, v124, v208
.Lnb_odd_norescale:
	v_sub_f32_e32 v92, v92, v202
	v_sub_f32_e32 v93, v93, v202
	v_sub_f32_e32 v94, v94, v202
	v_sub_f32_e32 v95, v95, v202
	v_sub_f32_e32 v48, v48, v202
	v_sub_f32_e32 v49, v49, v202
	v_sub_f32_e32 v50, v50, v202
	v_sub_f32_e32 v51, v51, v202
	v_sub_f32_e32 v52, v52, v202
	v_sub_f32_e32 v53, v53, v202
	v_sub_f32_e32 v54, v54, v202
	v_sub_f32_e32 v55, v55, v202
	v_sub_f32_e32 v56, v56, v202
	v_sub_f32_e32 v57, v57, v202
	v_sub_f32_e32 v58, v58, v202
	v_sub_f32_e32 v59, v59, v202
	v_sub_f32_e32 v60, v60, v202
	v_sub_f32_e32 v61, v61, v202
	v_sub_f32_e32 v62, v62, v202
	v_sub_f32_e32 v63, v63, v202
	v_mov_b32_e32 v36, 0
	v_mov_b32_e32 v37, 0
	v_exp_f32_e32 v92, v92
	v_exp_f32_e32 v93, v93
	v_exp_f32_e32 v94, v94
	v_exp_f32_e32 v95, v95
	s_nop 0
	v_cvt_pk_bf16_f32 v38, v92, v93
	v_cvt_pk_bf16_f32 v39, v94, v95
	s_nop 1
	s_waitcnt lgkmcnt(0)
	v_mfma_f32_32x32x16_bf16 v[0:15], v[164:167], v[36:39], v[0:15]
	v_exp_f32_e32 v48, v48
	v_exp_f32_e32 v49, v49
	v_exp_f32_e32 v50, v50
	v_exp_f32_e32 v51, v51
	v_mfma_f32_32x32x16_bf16 v[16:31], v[180:183], v[36:39], v[16:31]
	v_exp_f32_e32 v52, v52
	v_exp_f32_e32 v53, v53
	v_exp_f32_e32 v54, v54
	v_exp_f32_e32 v55, v55
	s_nop 0
	v_cvt_pk_bf16_f32 v40, v48, v49
	v_cvt_pk_bf16_f32 v41, v50, v51
	v_cvt_pk_bf16_f32 v42, v52, v53
	v_cvt_pk_bf16_f32 v43, v54, v55
	v_mov_b32_e32 v204, v92
	v_mov_b32_e32 v205, v93
	v_mov_b32_e32 v208, v94
	v_mov_b32_e32 v209, v95
	v_mfma_f32_32x32x16_bf16 v[0:15], v[168:171], v[40:43], v[0:15]
	v_exp_f32_e32 v56, v56
	v_exp_f32_e32 v57, v57
	v_exp_f32_e32 v58, v58
	v_exp_f32_e32 v59, v59
	v_mfma_f32_32x32x16_bf16 v[16:31], v[184:187], v[40:43], v[16:31]
	v_exp_f32_e32 v60, v60
	v_exp_f32_e32 v61, v61
	v_exp_f32_e32 v62, v62
	v_exp_f32_e32 v63, v63
	s_nop 0
	v_cvt_pk_bf16_f32 v44, v56, v57
	v_cvt_pk_bf16_f32 v45, v58, v59
	v_cvt_pk_bf16_f32 v46, v60, v61
	v_cvt_pk_bf16_f32 v47, v62, v63
	v_add_f32_e32 v204, v204, v48
	v_add_f32_e32 v205, v205, v49
	v_add_f32_e32 v208, v208, v50
	v_add_f32_e32 v209, v209, v51
	v_add_f32_e32 v204, v204, v52
	v_add_f32_e32 v205, v205, v53
	v_add_f32_e32 v208, v208, v54
	v_add_f32_e32 v209, v209, v55
	v_mfma_f32_32x32x16_bf16 v[0:15], v[172:175], v[44:47], v[0:15]
	v_mfma_f32_32x32x16_bf16 v[16:31], v[188:191], v[44:47], v[16:31]
	v_add_f32_e32 v204, v204, v56
	v_add_f32_e32 v205, v205, v57
	v_add_f32_e32 v208, v208, v58
	v_add_f32_e32 v209, v209, v59
	v_add_f32_e32 v204, v204, v60
	v_add_f32_e32 v205, v205, v61
	v_add_f32_e32 v208, v208, v62
	v_add_f32_e32 v209, v209, v63
	v_add_f32_e32 v204, v204, v205
	v_add_f32_e32 v208, v208, v209
	v_add_f32_e32 v204, v204, v208
	v_add_f32_e32 v124, v124, v204
	s_branch .Lmsk_tail

; __device__ __forceinline__ void attn_unit(int uv, const float* sink_l, const bf16_t* P, bf16_t* Y, ATT_LAS unsigned char* lds, const float* rpb_l, const float* qn_l, const float* kn_l) {
;     ...
;                 const float mt = rowmax32(p0, p1);
;                 if (__any(mt > m)) { const float mn = fmaxf(m, mt), alpha = __builtin_amdgcn_exp2f(m - mn); m = mn; lsum *= alpha;
; #pragma unroll
;                     for (int r = 0; r < 16; ++r) { o0[r] *= alpha; o1[r] *= alpha; } }
.Lwe_soft:
	v_max3_f32 v204, v80, v84, v88
	v_max3_f32 v205, v81, v85, v89
	v_max3_f32 v208, v82, v86, v90
	v_max3_f32 v209, v83, v87, v91
	v_max3_f32 v204, v204, v92, v48
	v_max3_f32 v205, v205, v93, v49
	v_max3_f32 v208, v208, v94, v50
	v_max3_f32 v209, v209, v95, v51
	v_max3_f32 v204, v204, v52, v56
	v_max3_f32 v205, v205, v53, v57
	v_max3_f32 v208, v208, v54, v58
	v_max3_f32 v209, v209, v55, v59
	v_max_f32_e32 v204, v204, v60
	v_max_f32_e32 v205, v205, v61
	v_max_f32_e32 v208, v208, v62
	v_max_f32_e32 v209, v209, v63
	v_max3_f32 v204, v204, v205, v208
	v_max_f32_e32 v204, v204, v209
	v_mov_b32_e32 v205, v204
	s_nop 1
	v_permlane32_swap_b32_e32 v204, v205
	v_max_f32_e32 v204, v204, v205
	v_add_f32_e32 v205, 0x41000000, v202
	v_cmp_gt_f32_e32 vcc, v204, v205
	s_cbranch_vccz .Lnb_we_norescale
	v_max_f32_e32 v205, v202, v204
	v_sub_f32_e32 v208, v202, v205
	v_exp_f32_e32 v208, v208
	v_mov_b32_e32 v202, v205
	v_pk_mul_f32 v[0:1], v[0:1], v[208:209] op_sel_hi:[1,0]
	v_pk_mul_f32 v[2:3], v[2:3], v[208:209] op_sel_hi:[1,0]
	v_pk_mul_f32 v[4:5], v[4:5], v[208:209] op_sel_hi:[1,0]
	v_pk_mul_f32 v[6:7], v[6:7], v[208:209] op_sel_hi:[1,0]
	v_pk_mul_f32 v[8:9], v[8:9], v[208:209] op_sel_hi:[1,0]
	v_pk_mul_f32 v[10:11], v[10:11], v[208:209] op_sel_hi:[1,0]
	v_pk_mul_f32 v[12:13], v[12:13], v[208:209] op_sel_hi:[1,0]
	v_pk_mul_f32 v[14:15], v[14:15], v[208:209] op_sel_hi:[1,0]
	v_pk_mul_f32 v[16:17], v[16:17], v[208:209] op_sel_hi:[1,0]
	v_pk_mul_f32 v[18:19], v[18:19], v[208:209] op_sel_hi:[1,0]
	v_pk_mul_f32 v[20:21], v[20:21], v[208:209] op_sel_hi:[1,0]
	v_pk_mul_f32 v[22:23], v[22:23], v[208:209] op_sel_hi:[1,0]
	v_pk_mul_f32 v[24:25], v[24:25], v[208:209] op_sel_hi:[1,0]
	v_pk_mul_f32 v[26:27], v[26:27], v[208:209] op_sel_hi:[1,0]
	v_pk_mul_f32 v[28:29], v[28:29], v[208:209] op_sel_hi:[1,0]
	v_pk_mul_f32 v[30:31], v[30:31], v[208:209] op_sel_hi:[1,0]
	v_mul_f32_e32 v124, v124, v208
